# P6 K-loop: same 4/4 LDS-DMA staging balance + SGPR-base DMA form as the other GEMM loops
# baseline (speedup 1.0000x reference)
; #define PG8_STAGE(bufoff, gbase, voff) do { _Pragma("unroll") for (int _i = 0; _i < 2; ++_i) \
;         __builtin_amdgcn_global_load_lds((const unsigned*)((const char*)(gbase) + (voff)[_i]), (PG8_LAS unsigned*)(lds + (bufoff) + ldsw + _i * 8192), 16, 0, 0); } while (0)
; #define PG8_LDA(dst, b, h) do { _Pragma("unroll") for (int m = 0; m < 4; ++m) _Pragma("unroll") for (int k = 0; k < 2; ++k) dst[m][k] = *(const PG8_LAS bf16x8*)(lds + PG8_SA(b, h) + aoff + m * 2048 + k * 1024); } while (0)
; #define PG8_LDB(dst, b, h) do { _Pragma("unroll") for (int n = 0; n < 2; ++n) _Pragma("unroll") for (int k = 0; k < 2; ++k) dst[n][k] = *(const PG8_LAS bf16x8*)(lds + PG8_SB(b, h) + boff + n * 2048 + k * 1024); } while (0)
; #define PG8_MMA(ai, bj, At, Bt) do { __builtin_amdgcn_s_setprio(1); _Pragma("unroll") for (int m = 0; m < 4; ++m) _Pragma("unroll") for (int n = 0; n < 2; ++n) _Pragma("unroll") for (int k = 0; k < 2; ++k) \
;         acc[ai][bj][m][n] = __builtin_amdgcn_mfma_f32_16x16x32_bf16(Bt[n][k], At[m][k], acc[ai][bj][m][n], 0, 0, 0); __builtin_amdgcn_s_setprio(0); } while (0)
; #define PG8_WAIT_V(n) asm volatile("s_waitcnt vmcnt(" #n ")" ::: "memory")
; #define PG8_WAIT_L(n) asm volatile("s_waitcnt lgkmcnt(" #n ")" ::: "memory")
; #define PG8_BAR __builtin_amdgcn_s_barrier()
; #define PG8_SCHED __builtin_amdgcn_sched_barrier(0)
; template <class Epi, class Sched, bool ALIGN_EPI = false, bool SP2 = false>
; __device__ __forceinline__ void gemm_phase(PG8_LAS unsigned char* lds, const Gemm g, const Sched& S, const Epi& E) {
;     ...
;             PG8_LDB(B0, 0, 0); PG8_LDB(B1, 0, 1); PG8_SCHED; PG8_LDA(At, 0, 0); PG8_STAGE(PG8_SA(1, 1), a1 + hstepA, voffA);
;             PG8_WAIT_V(8); PG8_WAIT_L(0); PG8_BAR; PG8_MMA(0, 0, At, B0); PG8_MMA(0, 1, At, B1); PG8_BAR; PG8_SCHED;
;             PG8_LDA(At, 0, 1); PG8_STAGE(PG8_SB(0, 0), b2, voffB); PG8_STAGE(PG8_SB(0, 1), b2 + hstepB, voffB); PG8_STAGE(PG8_SA(0, 0), a2, voffA);
;             PG8_WAIT_V(8); PG8_WAIT_L(0); PG8_BAR; PG8_MMA(1, 0, At, B0); PG8_MMA(1, 1, At, B1); PG8_BAR; PG8_SCHED;
.LBB0_1738:
	ds_read_b128 v[144:147], v151
	ds_read_b128 v[154:157], v151 offset:1024
	ds_read_b128 v[158:161], v151 offset:2048
	ds_read_b128 v[162:165], v151 offset:3072
	ds_read_b128 v[166:169], v152
	ds_read_b128 v[170:173], v152 offset:1024
	ds_read_b128 v[174:177], v152 offset:2048
	ds_read_b128 v[178:181], v152 offset:3072
	s_add_u32 s34, s20, 0xfffe0080
	s_addc_u32 s35, s21, -1
	s_cmp_eq_u32 s57, 4
	s_cselect_b32 s39, s13, s35
	s_cselect_b32 s38, s27, s34
	s_cselect_b32 s35, s25, s56
	s_cselect_b32 s34, s52, s53
	s_add_i32 m0, s5, 0xc000
	ds_read_b128 v[182:185], v153
	ds_read_b128 v[186:189], v153 offset:1024
	ds_read_b128 v[190:193], v153 offset:2048
	ds_read_b128 v[194:197], v153 offset:3072
	ds_read_b128 v[198:201], v153 offset:4096
	ds_read_b128 v[202:205], v153 offset:5120
	ds_read_b128 v[206:209], v153 offset:6144
	ds_read_b128 v[210:213], v153 offset:7168
	s_add_u32 s98, s20, 0xfffe0000
	s_addc_u32 s99, s21, -1
	s_mov_b32 m0, s42
	s_nop 0
	global_load_lds_dwordx4 v128, s[98:99]
	s_mov_b32 m0, s43
	s_nop 0
	global_load_lds_dwordx4 v132, s[98:99]
	s_add_i32 m0, s5, 0xc000
	s_nop 0
	global_load_lds_dwordx4 v136, s[20:21]
	s_add_i32 m0, s5, 0xe000
	s_nop 0
	global_load_lds_dwordx4 v138, s[20:21]
	s_waitcnt vmcnt(8)
	s_waitcnt lgkmcnt(0)
	s_barrier
	s_setprio 1
	s_waitcnt lgkmcnt(0)
	v_mfma_f32_16x16x32_bf16 v[124:127], v[144:147], v[182:185], v[124:127]
	v_mfma_f32_16x16x32_bf16 v[120:123], v[158:161], v[182:185], v[120:123]
	v_mfma_f32_16x16x32_bf16 v[108:111], v[144:147], v[190:193], v[108:111]
	v_mfma_f32_16x16x32_bf16 v[104:107], v[158:161], v[190:193], v[104:107]
	v_mfma_f32_16x16x32_bf16 v[92:95], v[144:147], v[198:201], v[92:95]
	v_mfma_f32_16x16x32_bf16 v[88:91], v[158:161], v[198:201], v[88:91]
	v_mfma_f32_16x16x32_bf16 v[76:79], v[144:147], v[206:209], v[76:79]
	v_mfma_f32_16x16x32_bf16 v[72:75], v[158:161], v[206:209], v[72:75]
	v_mfma_f32_16x16x32_bf16 v[124:127], v[154:157], v[186:189], v[124:127]
	v_mfma_f32_16x16x32_bf16 v[120:123], v[162:165], v[186:189], v[120:123]
	v_mfma_f32_16x16x32_bf16 v[108:111], v[154:157], v[194:197], v[108:111]
	v_mfma_f32_16x16x32_bf16 v[104:107], v[162:165], v[194:197], v[104:107]
	v_mfma_f32_16x16x32_bf16 v[92:95], v[154:157], v[202:205], v[92:95]
	v_mfma_f32_16x16x32_bf16 v[88:91], v[162:165], v[202:205], v[88:91]
	v_mfma_f32_16x16x32_bf16 v[76:79], v[154:157], v[210:213], v[76:79]
	v_mfma_f32_16x16x32_bf16 v[72:75], v[162:165], v[210:213], v[72:75]
	s_setprio 0
	s_setprio 1
	v_mfma_f32_16x16x32_bf16 v[116:119], v[166:169], v[182:185], v[116:119]
	v_mfma_f32_16x16x32_bf16 v[112:115], v[174:177], v[182:185], v[112:115]
	v_mfma_f32_16x16x32_bf16 v[100:103], v[166:169], v[190:193], v[100:103]
	v_mfma_f32_16x16x32_bf16 v[96:99], v[174:177], v[190:193], v[96:99]
	v_mfma_f32_16x16x32_bf16 v[84:87], v[166:169], v[198:201], v[84:87]
	v_mfma_f32_16x16x32_bf16 v[80:83], v[174:177], v[198:201], v[80:83]
	v_mfma_f32_16x16x32_bf16 v[68:71], v[166:169], v[206:209], v[68:71]
	v_mfma_f32_16x16x32_bf16 v[64:67], v[174:177], v[206:209], v[64:67]
	v_mfma_f32_16x16x32_bf16 v[116:119], v[170:173], v[186:189], v[116:119]
	v_mfma_f32_16x16x32_bf16 v[112:115], v[178:181], v[186:189], v[112:115]
	v_mfma_f32_16x16x32_bf16 v[100:103], v[170:173], v[194:197], v[100:103]
	v_mfma_f32_16x16x32_bf16 v[96:99], v[178:181], v[194:197], v[96:99]
	v_mfma_f32_16x16x32_bf16 v[84:87], v[170:173], v[202:205], v[84:87]
	v_mfma_f32_16x16x32_bf16 v[80:83], v[178:181], v[202:205], v[80:83]
	v_mfma_f32_16x16x32_bf16 v[68:71], v[170:173], v[210:213], v[68:71]
	v_mfma_f32_16x16x32_bf16 v[64:67], v[178:181], v[210:213], v[64:67]
	s_setprio 0
	s_barrier
	s_add_i32 s58, s47, s4
	s_mov_b32 m0, s58
	ds_read_b128 v[182:185], v153 offset:16384
	ds_read_b128 v[186:189], v153 offset:17408
	ds_read_b128 v[190:193], v153 offset:18432
	ds_read_b128 v[194:197], v153 offset:19456
	ds_read_b128 v[198:201], v153 offset:20480
	ds_read_b128 v[202:205], v153 offset:21504
	ds_read_b128 v[206:209], v153 offset:22528
	ds_read_b128 v[210:213], v153 offset:23552
	global_load_lds_dwordx4 v130, s[34:35]
	s_add_i32 m0, s58, 0x2000
	s_add_u32 s58, s34, 0x20000
	s_addc_u32 s59, s35, 0
	s_add_i32 s60, s50, s4
	global_load_lds_dwordx4 v134, s[34:35]
	s_mov_b32 m0, s60
	s_nop 0
	global_load_lds_dwordx4 v130, s[58:59]
	s_add_i32 m0, s60, 0x2000
	s_nop 0
	global_load_lds_dwordx4 v134, s[58:59]
	s_waitcnt vmcnt(6)
	s_waitcnt lgkmcnt(0)
	s_barrier
	s_setprio 1
	s_waitcnt lgkmcnt(0)
	v_mfma_f32_16x16x32_bf16 v[60:63], v[144:147], v[182:185], v[60:63]
	v_mfma_f32_16x16x32_bf16 v[56:59], v[158:161], v[182:185], v[56:59]
	v_mfma_f32_16x16x32_bf16 v[44:47], v[144:147], v[190:193], v[44:47]
	v_mfma_f32_16x16x32_bf16 v[40:43], v[158:161], v[190:193], v[40:43]
	v_mfma_f32_16x16x32_bf16 v[28:31], v[144:147], v[198:201], v[28:31]
	v_mfma_f32_16x16x32_bf16 v[24:27], v[158:161], v[198:201], v[24:27]
	v_mfma_f32_16x16x32_bf16 v[12:15], v[144:147], v[206:209], v[12:15]
	v_mfma_f32_16x16x32_bf16 v[8:11], v[158:161], v[206:209], v[8:11]
	v_mfma_f32_16x16x32_bf16 v[60:63], v[154:157], v[186:189], v[60:63]
	v_mfma_f32_16x16x32_bf16 v[56:59], v[162:165], v[186:189], v[56:59]
	v_mfma_f32_16x16x32_bf16 v[44:47], v[154:157], v[194:197], v[44:47]
	v_mfma_f32_16x16x32_bf16 v[40:43], v[162:165], v[194:197], v[40:43]
	v_mfma_f32_16x16x32_bf16 v[28:31], v[154:157], v[202:205], v[28:31]
	v_mfma_f32_16x16x32_bf16 v[24:27], v[162:165], v[202:205], v[24:27]
	v_mfma_f32_16x16x32_bf16 v[12:15], v[154:157], v[210:213], v[12:15]
	v_mfma_f32_16x16x32_bf16 v[8:11], v[162:165], v[210:213], v[8:11]
	s_setprio 0
	s_setprio 1
	v_mfma_f32_16x16x32_bf16 v[52:55], v[166:169], v[182:185], v[52:55]
	v_mfma_f32_16x16x32_bf16 v[48:51], v[174:177], v[182:185], v[48:51]
	v_mfma_f32_16x16x32_bf16 v[36:39], v[166:169], v[190:193], v[36:39]
	v_mfma_f32_16x16x32_bf16 v[32:35], v[174:177], v[190:193], v[32:35]
	v_mfma_f32_16x16x32_bf16 v[20:23], v[166:169], v[198:201], v[20:23]
	v_mfma_f32_16x16x32_bf16 v[16:19], v[174:177], v[198:201], v[16:19]
	v_mfma_f32_16x16x32_bf16 v[4:7], v[166:169], v[206:209], v[4:7]
	v_mfma_f32_16x16x32_bf16 v[0:3], v[174:177], v[206:209], v[0:3]
	v_mfma_f32_16x16x32_bf16 v[52:55], v[170:173], v[186:189], v[52:55]
	v_mfma_f32_16x16x32_bf16 v[48:51], v[178:181], v[186:189], v[48:51]
	v_mfma_f32_16x16x32_bf16 v[36:39], v[170:173], v[194:197], v[36:39]
	v_mfma_f32_16x16x32_bf16 v[32:35], v[178:181], v[194:197], v[32:35]
	v_mfma_f32_16x16x32_bf16 v[20:23], v[170:173], v[202:205], v[20:23]
	v_mfma_f32_16x16x32_bf16 v[16:19], v[178:181], v[202:205], v[16:19]
	v_mfma_f32_16x16x32_bf16 v[4:7], v[170:173], v[210:213], v[4:7]
	v_mfma_f32_16x16x32_bf16 v[0:3], v[178:181], v[210:213], v[0:3]
	s_setprio 0
	s_barrier
; #define PG8_STAGE(bufoff, gbase, voff) do { _Pragma("unroll") for (int _i = 0; _i < 2; ++_i) \
;         __builtin_amdgcn_global_load_lds((const unsigned*)((const char*)(gbase) + (voff)[_i]), (PG8_LAS unsigned*)(lds + (bufoff) + ldsw + _i * 8192), 16, 0, 0); } while (0)
; #define PG8_LDA(dst, b, h) do { _Pragma("unroll") for (int m = 0; m < 4; ++m) _Pragma("unroll") for (int k = 0; k < 2; ++k) dst[m][k] = *(const PG8_LAS bf16x8*)(lds + PG8_SA(b, h) + aoff + m * 2048 + k * 1024); } while (0)
; #define PG8_LDB(dst, b, h) do { _Pragma("unroll") for (int n = 0; n < 2; ++n) _Pragma("unroll") for (int k = 0; k < 2; ++k) dst[n][k] = *(const PG8_LAS bf16x8*)(lds + PG8_SB(b, h) + boff + n * 2048 + k * 1024); } while (0)
; #define PG8_MMA(ai, bj, At, Bt) do { __builtin_amdgcn_s_setprio(1); _Pragma("unroll") for (int m = 0; m < 4; ++m) _Pragma("unroll") for (int n = 0; n < 2; ++n) _Pragma("unroll") for (int k = 0; k < 2; ++k) \
;         acc[ai][bj][m][n] = __builtin_amdgcn_mfma_f32_16x16x32_bf16(Bt[n][k], At[m][k], acc[ai][bj][m][n], 0, 0, 0); __builtin_amdgcn_s_setprio(0); } while (0)
; #define PG8_WAIT_V(n) asm volatile("s_waitcnt vmcnt(" #n ")" ::: "memory")
; #define PG8_WAIT_L(n) asm volatile("s_waitcnt lgkmcnt(" #n ")" ::: "memory")
; #define PG8_BAR __builtin_amdgcn_s_barrier()
; #define PG8_SCHED __builtin_amdgcn_sched_barrier(0)
; template <class Epi, class Sched, bool ALIGN_EPI = false, bool SP2 = false>
; __device__ __forceinline__ void gemm_phase(PG8_LAS unsigned char* lds, const Gemm g, const Sched& S, const Epi& E) {
;     ...
;             PG8_LDB(B0, 1, 0); PG8_LDB(B1, 1, 1); PG8_SCHED; PG8_LDA(At, 1, 0); PG8_STAGE(PG8_SA(0, 1), a2 + hstepA, voffA);
;             PG8_WAIT_V(8); PG8_WAIT_L(0); PG8_BAR; PG8_MMA(0, 0, At, B0); PG8_MMA(0, 1, At, B1); PG8_BAR; PG8_SCHED;
;             PG8_LDA(At, 1, 1); PG8_STAGE(PG8_SB(1, 0), b3, voffB); PG8_STAGE(PG8_SB(1, 1), b3 + hstepB, voffB); PG8_STAGE(PG8_SA(1, 0), a3, voffA);
;             PG8_WAIT_V(8); PG8_WAIT_L(0); PG8_BAR; PG8_MMA(1, 0, At, B0); PG8_MMA(1, 1, At, B1); PG8_BAR; PG8_SCHED;
	s_add_i32 s58, 0, 0x18000
	s_add_i32 s59, 0, 0x1c000
	v_add_u32_e32 v162, s58, v150
	v_add_u32_e32 v178, s59, v150
	ds_read_b128 v[144:147], v162
	ds_read_b128 v[154:157], v162 offset:1024
	ds_read_b128 v[158:161], v162 offset:2048
	ds_read_b128 v[162:165], v162 offset:3072
	ds_read_b128 v[166:169], v178
	ds_read_b128 v[170:173], v178 offset:1024
	ds_read_b128 v[174:177], v178 offset:2048
	ds_read_b128 v[178:181], v178 offset:3072
	s_mov_b64 s[100:101], s[38:39]
	s_add_u32 s38, s38, 0x20000
	s_addc_u32 s39, s39, 0
	s_mov_b32 m0, s7
	ds_read_b128 v[182:185], v153 offset:32768
	ds_read_b128 v[186:189], v153 offset:33792
	ds_read_b128 v[190:193], v153 offset:34816
	ds_read_b128 v[194:197], v153 offset:35840
	ds_read_b128 v[198:201], v153 offset:36864
	ds_read_b128 v[202:205], v153 offset:37888
	ds_read_b128 v[206:209], v153 offset:38912
	ds_read_b128 v[210:213], v153 offset:39936
	s_mov_b32 m0, s5
	s_nop 0
	global_load_lds_dwordx4 v128, s[100:101]
	s_mov_b32 m0, s6
	s_nop 0
	global_load_lds_dwordx4 v132, s[100:101]
	s_mov_b32 m0, s7
	s_nop 0
	global_load_lds_dwordx4 v128, s[38:39]
	s_mov_b32 m0, s33
	s_nop 0
	global_load_lds_dwordx4 v132, s[38:39]
	s_waitcnt vmcnt(8)
	s_waitcnt lgkmcnt(0)
	s_barrier
	s_setprio 1
	s_waitcnt lgkmcnt(0)
	v_mfma_f32_16x16x32_bf16 v[124:127], v[144:147], v[182:185], v[124:127]
	v_mfma_f32_16x16x32_bf16 v[120:123], v[158:161], v[182:185], v[120:123]
	v_mfma_f32_16x16x32_bf16 v[108:111], v[144:147], v[190:193], v[108:111]
	v_mfma_f32_16x16x32_bf16 v[104:107], v[158:161], v[190:193], v[104:107]
	v_mfma_f32_16x16x32_bf16 v[92:95], v[144:147], v[198:201], v[92:95]
	v_mfma_f32_16x16x32_bf16 v[88:91], v[158:161], v[198:201], v[88:91]
	v_mfma_f32_16x16x32_bf16 v[76:79], v[144:147], v[206:209], v[76:79]
	v_mfma_f32_16x16x32_bf16 v[72:75], v[158:161], v[206:209], v[72:75]
	v_mfma_f32_16x16x32_bf16 v[124:127], v[154:157], v[186:189], v[124:127]
	v_mfma_f32_16x16x32_bf16 v[120:123], v[162:165], v[186:189], v[120:123]
	v_mfma_f32_16x16x32_bf16 v[108:111], v[154:157], v[194:197], v[108:111]
	v_mfma_f32_16x16x32_bf16 v[104:107], v[162:165], v[194:197], v[104:107]
	v_mfma_f32_16x16x32_bf16 v[92:95], v[154:157], v[202:205], v[92:95]
	v_mfma_f32_16x16x32_bf16 v[88:91], v[162:165], v[202:205], v[88:91]
	v_mfma_f32_16x16x32_bf16 v[76:79], v[154:157], v[210:213], v[76:79]
	v_mfma_f32_16x16x32_bf16 v[72:75], v[162:165], v[210:213], v[72:75]
	s_setprio 0
	s_setprio 1
	v_mfma_f32_16x16x32_bf16 v[116:119], v[166:169], v[182:185], v[116:119]
	v_mfma_f32_16x16x32_bf16 v[112:115], v[174:177], v[182:185], v[112:115]
	v_mfma_f32_16x16x32_bf16 v[100:103], v[166:169], v[190:193], v[100:103]
	v_mfma_f32_16x16x32_bf16 v[96:99], v[174:177], v[190:193], v[96:99]
	v_mfma_f32_16x16x32_bf16 v[84:87], v[166:169], v[198:201], v[84:87]
	v_mfma_f32_16x16x32_bf16 v[80:83], v[174:177], v[198:201], v[80:83]
	v_mfma_f32_16x16x32_bf16 v[68:71], v[166:169], v[206:209], v[68:71]
	v_mfma_f32_16x16x32_bf16 v[64:67], v[174:177], v[206:209], v[64:67]
	v_mfma_f32_16x16x32_bf16 v[116:119], v[170:173], v[186:189], v[116:119]
	v_mfma_f32_16x16x32_bf16 v[112:115], v[178:181], v[186:189], v[112:115]
	v_mfma_f32_16x16x32_bf16 v[100:103], v[170:173], v[194:197], v[100:103]
	v_mfma_f32_16x16x32_bf16 v[96:99], v[178:181], v[194:197], v[96:99]
	v_mfma_f32_16x16x32_bf16 v[84:87], v[170:173], v[202:205], v[84:87]
	v_mfma_f32_16x16x32_bf16 v[80:83], v[178:181], v[202:205], v[80:83]
	v_mfma_f32_16x16x32_bf16 v[68:71], v[170:173], v[210:213], v[68:71]
	v_mfma_f32_16x16x32_bf16 v[64:67], v[178:181], v[210:213], v[64:67]
	s_setprio 0
	s_barrier
	s_add_i32 s38, s58, s4
	s_add_u32 s98, s34, 0x80
	s_addc_u32 s99, s35, 0
	s_mov_b32 m0, s38
	ds_read_b128 v[182:185], v153 offset:49152
	ds_read_b128 v[186:189], v153 offset:50176
	ds_read_b128 v[190:193], v153 offset:51200
	ds_read_b128 v[194:197], v153 offset:52224
	ds_read_b128 v[198:201], v153 offset:53248
	ds_read_b128 v[202:205], v153 offset:54272
	ds_read_b128 v[206:209], v153 offset:55296
	ds_read_b128 v[210:213], v153 offset:56320
	global_load_lds_dwordx4 v130, s[98:99]
	s_add_i32 m0, s38, 0x2000
	s_add_u32 s34, s34, 0x20080
	s_addc_u32 s35, s35, 0
	s_add_i32 s38, s59, s4
	global_load_lds_dwordx4 v134, s[98:99]
	s_mov_b32 m0, s38
	s_nop 0
	global_load_lds_dwordx4 v130, s[34:35]
	s_add_i32 m0, s38, 0x2000
	s_nop 0
	global_load_lds_dwordx4 v134, s[34:35]
	s_waitcnt vmcnt(6)
	s_waitcnt lgkmcnt(0)
	s_barrier
	s_setprio 1
	s_waitcnt lgkmcnt(0)
	v_mfma_f32_16x16x32_bf16 v[60:63], v[144:147], v[182:185], v[60:63]
	v_mfma_f32_16x16x32_bf16 v[56:59], v[158:161], v[182:185], v[56:59]
	v_mfma_f32_16x16x32_bf16 v[44:47], v[144:147], v[190:193], v[44:47]
	v_mfma_f32_16x16x32_bf16 v[40:43], v[158:161], v[190:193], v[40:43]
	v_mfma_f32_16x16x32_bf16 v[28:31], v[144:147], v[198:201], v[28:31]
	v_mfma_f32_16x16x32_bf16 v[24:27], v[158:161], v[198:201], v[24:27]
	v_mfma_f32_16x16x32_bf16 v[12:15], v[144:147], v[206:209], v[12:15]
	v_mfma_f32_16x16x32_bf16 v[8:11], v[158:161], v[206:209], v[8:11]
	v_mfma_f32_16x16x32_bf16 v[60:63], v[154:157], v[186:189], v[60:63]
	v_mfma_f32_16x16x32_bf16 v[56:59], v[162:165], v[186:189], v[56:59]
	v_mfma_f32_16x16x32_bf16 v[44:47], v[154:157], v[194:197], v[44:47]
	v_mfma_f32_16x16x32_bf16 v[40:43], v[162:165], v[194:197], v[40:43]
	v_mfma_f32_16x16x32_bf16 v[28:31], v[154:157], v[202:205], v[28:31]
	v_mfma_f32_16x16x32_bf16 v[24:27], v[162:165], v[202:205], v[24:27]
	v_mfma_f32_16x16x32_bf16 v[12:15], v[154:157], v[210:213], v[12:15]
	v_mfma_f32_16x16x32_bf16 v[8:11], v[162:165], v[210:213], v[8:11]
	s_setprio 0
	s_setprio 1
	v_mfma_f32_16x16x32_bf16 v[52:55], v[166:169], v[182:185], v[52:55]
	v_mfma_f32_16x16x32_bf16 v[48:51], v[174:177], v[182:185], v[48:51]
	v_mfma_f32_16x16x32_bf16 v[36:39], v[166:169], v[190:193], v[36:39]
	v_mfma_f32_16x16x32_bf16 v[32:35], v[174:177], v[190:193], v[32:35]
	v_mfma_f32_16x16x32_bf16 v[20:23], v[166:169], v[198:201], v[20:23]
	v_mfma_f32_16x16x32_bf16 v[16:19], v[174:177], v[198:201], v[16:19]
	v_mfma_f32_16x16x32_bf16 v[4:7], v[166:169], v[206:209], v[4:7]
	v_mfma_f32_16x16x32_bf16 v[0:3], v[174:177], v[206:209], v[0:3]
	v_mfma_f32_16x16x32_bf16 v[52:55], v[170:173], v[186:189], v[52:55]
	v_mfma_f32_16x16x32_bf16 v[48:51], v[178:181], v[186:189], v[48:51]
	v_mfma_f32_16x16x32_bf16 v[36:39], v[170:173], v[194:197], v[36:39]
	v_mfma_f32_16x16x32_bf16 v[32:35], v[178:181], v[194:197], v[32:35]
	v_mfma_f32_16x16x32_bf16 v[20:23], v[170:173], v[202:205], v[20:23]
	v_mfma_f32_16x16x32_bf16 v[16:19], v[178:181], v[202:205], v[16:19]
	v_mfma_f32_16x16x32_bf16 v[4:7], v[170:173], v[210:213], v[4:7]
	v_mfma_f32_16x16x32_bf16 v[0:3], v[178:181], v[210:213], v[0:3]
	s_setprio 0
	s_barrier
	s_add_i32 s57, s57, 2
	s_add_u32 s20, s20, 0x100
	s_addc_u32 s21, s21, 0
	s_add_u32 s53, s53, 0x100
	s_addc_u32 s56, s56, 0
	s_cmp_gt_u32 s57, 5
	s_cbranch_scc0 .LBB0_1738
	s_and_b64 vcc, exec, s[22:23]
	s_cbranch_vccz .LBB0_1741
	s_barrier
